# final RMSNorm: gains loaded once per wave, all row loads up front, 8 stores at the end (was 9 serialized round trips per row)
# speedup vs baseline: 1.0035x; 1.0035x over previous
; __global__ void __launch_bounds__(512, 2) mk_fwd(Params p) {
;     ...
;         } else if (ph == N_PHASES - 1) {
;             for (int m = gw; m < M; m += NGW) {
;                 f32x4* xr = (f32x4*)(p.out + (size_t)m * DM) + lane; const f32x4* wr_ = (const f32x4*)p.fnorm + lane; const v2u* xb8 = (const v2u*)(XB + (size_t)m * DM) + lane;
;                 const float rstd = 1.0f / sqrtf(wave_sum(lane < 32 ? ROWSQ[((size_t)DEPTH * M + m) * 32 + lane] : 0.f) * (1.0f / DM) + EPS);
; #pragma unroll
.LBB0_22:
	s_ashr_i32 s48, s0, 6
	s_lshl_b32 s0, s99, 3
	s_mov_b64 s[28:29], 0
	s_add_i32 s24, s0, s48
	s_lshl_b32 s26, s98, 3
	s_add_u32 s94, s72, s28
	s_addc_u32 s95, s73, s29
	s_add_u32 s96, s94, 0x6800000
	s_addc_u32 s97, s95, 0
	v_and_b32_e32 v228, 63, v229
	s_mov_b64 s[16:17], -1
	s_mov_b64 s[2:3], 0
	s_cmp_lt_i32 s74, 21
	s_mov_b64 s[0:1], 0
	s_cbranch_scc1 .LBB0_29
	s_cmp_eq_u32 s74, 21
	s_mov_b64 s[0:1], -1
	s_cbranch_scc0 .LBB0_33
	s_cmpk_gt_i32 s24, 0x3fff
	s_cbranch_scc1 .LBB0_32
	v_cmp_lt_i32_e32 vcc, v220, v219
	v_lshlrev_b32_e32 v0, 4, v228
	v_lshl_add_u64 v[2:3], s[68:69], 0, v[0:1]
	v_cndmask_b32_e32 v4, v218, v220, vcc
	v_cmp_lt_i32_e32 vcc, v221, v219
	v_lshlrev_b32_e32 v18, 2, v4
	s_mov_b64 s[0:1], 0x1000
	v_cndmask_b32_e32 v4, v218, v221, vcc
	v_cmp_lt_i32_e32 vcc, v222, v219
	v_lshlrev_b32_e32 v19, 2, v4
	s_ashr_i32 s25, s24, 31
	v_cndmask_b32_e32 v4, v218, v222, vcc
	v_cmp_lt_i32_e32 vcc, v223, v219
	v_lshlrev_b32_e32 v20, 2, v4
	v_readlane_b32 s4, v255, 15
	v_cndmask_b32_e32 v4, v218, v223, vcc
	v_cmp_lt_i32_e32 vcc, v224, v219
	v_lshlrev_b32_e32 v21, 2, v4
	v_lshlrev_b32_e32 v12, 2, v228
	v_cndmask_b32_e32 v4, v218, v224, vcc
	v_cmp_lt_i32_e32 vcc, v225, v219
	v_lshlrev_b32_e32 v22, 2, v4
	v_mov_b32_e32 v13, v1
	v_cndmask_b32_e32 v4, v218, v225, vcc
	v_lshlrev_b32_e32 v23, 2, v4
	v_lshl_add_u64 v[4:5], v[2:3], 0, s[0:1]
	s_mov_b64 s[0:1], 0x1400
	v_lshl_add_u64 v[6:7], v[2:3], 0, s[0:1]
	s_mov_b64 s[0:1], 0x1800
	v_lshl_add_u64 v[8:9], v[2:3], 0, s[0:1]
	s_mov_b64 s[0:1], 0x1c00
	v_lshl_add_u64 v[10:11], v[2:3], 0, s[0:1]
	s_lshl_b64 s[0:1], s[24:25], 7
	s_add_u32 s0, s28, s0
	s_addc_u32 s1, s29, s1
	s_add_u32 s0, s4, s0
	v_readlane_b32 s4, v255, 16
	s_addc_u32 s1, s4, s1
	s_ashr_i32 s27, s26, 31
	v_lshl_add_u64 v[12:13], s[0:1], 0, v[12:13]
	s_lshl_b64 s[16:17], s[26:27], 7
	s_lshl_b64 s[0:1], s[24:25], 13
	v_readlane_b32 s4, v255, 17
	s_add_u32 s0, s4, s0
	v_readlane_b32 s4, v255, 18
	s_addc_u32 s1, s4, s1
	v_lshl_add_u64 v[14:15], s[0:1], 0, v[0:1]
	s_lshl_b64 s[18:19], s[26:27], 13
	s_lshl_b64 s[0:1], s[24:25], 12
	s_add_u32 s0, s28, s0
	s_addc_u32 s1, s29, s1
	v_readlane_b32 s4, v255, 19
	s_add_u32 s0, s4, s0
	v_readlane_b32 s4, v255, 20
	v_lshlrev_b32_e32 v0, 3, v228
	s_addc_u32 s1, s4, s1
	v_cmp_gt_u32_e64 s[38:39], 32, v228
	v_lshl_add_u64 v[16:17], s[0:1], 0, v[0:1]
	s_lshl_b64 s[20:21], s[26:27], 12
	s_mov_b32 s4, s24
	global_load_dwordx4 v[100:103], v[2:3], off
	global_load_dwordx4 v[104:107], v[2:3], off offset:1024
	global_load_dwordx4 v[108:111], v[2:3], off offset:2048
	global_load_dwordx4 v[112:115], v[2:3], off offset:3072
	global_load_dwordx4 v[116:119], v[4:5], off
	global_load_dwordx4 v[120:123], v[6:7], off
	global_load_dwordx4 v[124:127], v[8:9], off
	global_load_dwordx4 v[128:131], v[10:11], off
; __device__ __forceinline__ float bflo(unsigned w) { return __uint_as_float(w << 16); }
; __device__ __forceinline__ float bfhi(unsigned w) { return __uint_as_float(w & 0xffff0000u); }
; __global__ void __launch_bounds__(512, 2) mk_fwd(Params p) {
;     ...
;             for (int m = gw; m < M; m += NGW) {
;                 f32x4* xr = (f32x4*)(p.out + (size_t)m * DM) + lane; const f32x4* wr_ = (const f32x4*)p.fnorm + lane; const v2u* xb8 = (const v2u*)(XB + (size_t)m * DM) + lane;
;                 const float rstd = 1.0f / sqrtf(wave_sum(lane < 32 ? ROWSQ[((size_t)DEPTH * M + m) * 32 + lane] : 0.f) * (1.0f / DM) + EPS);
; #pragma unroll
;                 for (int j = 0; j < 8; ++j) { const v2u w = xb8[64 * j]; const f32x4 v = {bflo(w.x), bfhi(w.x), bflo(w.y), bfhi(w.y)}; xr[64 * j] = v * rstd * wr_[64 * j]; }
;             }
.LBB0_27:
	v_mov_b32_e32 v0, 0
	s_and_saveexec_b64 s[0:1], s[38:39]
	global_load_dword v0, v[12:13], off
	s_or_b64 exec, exec, s[0:1]
	global_load_dwordx2 v[40:41], v[16:17], off offset:-2048
	global_load_dwordx2 v[42:43], v[16:17], off offset:-1536
	global_load_dwordx2 v[44:45], v[16:17], off offset:-1024
	global_load_dwordx2 v[46:47], v[16:17], off offset:-512
	global_load_dwordx2 v[48:49], v[16:17], off
	global_load_dwordx2 v[50:51], v[16:17], off offset:512
	global_load_dwordx2 v[52:53], v[16:17], off offset:1024
	global_load_dwordx2 v[54:55], v[16:17], off offset:1536
	s_add_i32 s4, s4, s26
	v_lshl_add_u64 v[12:13], v[12:13], 0, s[16:17]
	v_lshl_add_u64 v[16:17], v[16:17], 0, s[20:21]
	s_waitcnt vmcnt(8)
	ds_bpermute_b32 v30, v18, v0
	s_waitcnt lgkmcnt(0)
	v_add_f32_e32 v0, v0, v30
	ds_bpermute_b32 v30, v19, v0
	s_waitcnt lgkmcnt(0)
	v_add_f32_e32 v0, v0, v30
	ds_bpermute_b32 v30, v20, v0
	s_waitcnt lgkmcnt(0)
	v_add_f32_e32 v0, v0, v30
	ds_bpermute_b32 v30, v21, v0
	s_waitcnt lgkmcnt(0)
	v_add_f32_e32 v0, v0, v30
	ds_bpermute_b32 v30, v22, v0
	s_waitcnt lgkmcnt(0)
	v_add_f32_e32 v0, v0, v30
	ds_bpermute_b32 v30, v23, v0
	s_waitcnt lgkmcnt(0)
	v_add_f32_e32 v0, v0, v30
	v_fmamk_f32 v0, v0, 0x3a000000, v215
	v_mul_f32_e32 v30, 0x4f800000, v0
	v_cmp_gt_f32_e32 vcc, s33, v0
	s_nop 1
	v_cndmask_b32_e32 v0, v0, v30, vcc
	v_sqrt_f32_e32 v30, v0
	s_nop 0
	v_add_u32_e32 v31, -1, v30
	v_add_u32_e32 v32, 1, v30
	v_fma_f32 v33, -v31, v30, v0
	v_fma_f32 v34, -v32, v30, v0
	v_cmp_ge_f32_e64 s[0:1], 0, v33
	s_nop 1
	v_cndmask_b32_e64 v30, v30, v31, s[0:1]
	v_cmp_lt_f32_e64 s[0:1], 0, v34
	s_nop 1
	v_cndmask_b32_e64 v30, v30, v32, s[0:1]
	v_mul_f32_e32 v31, 0x37800000, v30
	v_cndmask_b32_e32 v30, v30, v31, vcc
	v_cmp_class_f32_e32 vcc, v0, v216
	s_nop 1
	v_cndmask_b32_e32 v0, v30, v0, vcc
	v_div_scale_f32 v32, s[0:1], v0, v0, 1.0
	v_rcp_f32_e32 v33, v32
	s_nop 0
	v_fma_f32 v35, -v32, v33, 1.0
	s_nop 0
	v_div_scale_f32 v34, vcc, 1.0, v0, 1.0
	v_fmac_f32_e32 v33, v35, v33
	v_mul_f32_e32 v35, v34, v33
	v_fma_f32 v36, -v32, v35, v34
	v_fmac_f32_e32 v35, v36, v33
	v_fma_f32 v32, -v32, v35, v34
	v_div_fmas_f32 v32, v32, v33, v35
	v_div_fixup_f32 v0, v32, v0, 1.0
	s_movk_i32 s0, 0xf000
	v_add_co_u32_e32 v30, vcc, s0, v14
	s_nop 1
	v_addc_co_u32_e32 v31, vcc, -1, v15, vcc
	s_waitcnt vmcnt(7)
	v_lshlrev_b32_e32 v32, 16, v40
	v_and_b32_e32 v33, 0xffff0000, v40
	v_lshlrev_b32_e32 v28, 16, v41
	v_and_b32_e32 v29, 0xffff0000, v41
	v_pk_mul_f32 v[32:33], v[0:1], v[32:33] op_sel_hi:[0,1]
	v_pk_mul_f32 v[28:29], v[0:1], v[28:29] op_sel_hi:[0,1]
	v_pk_mul_f32 v[134:135], v[102:103], v[28:29]
	v_pk_mul_f32 v[132:133], v[100:101], v[32:33]
	s_waitcnt vmcnt(6)
	v_lshlrev_b32_e32 v32, 16, v42
	v_and_b32_e32 v33, 0xffff0000, v42
	v_lshlrev_b32_e32 v28, 16, v43
	v_and_b32_e32 v29, 0xffff0000, v43
	v_pk_mul_f32 v[32:33], v[0:1], v[32:33] op_sel_hi:[0,1]
	v_pk_mul_f32 v[28:29], v[0:1], v[28:29] op_sel_hi:[0,1]
	v_pk_mul_f32 v[138:139], v[106:107], v[28:29]
	v_pk_mul_f32 v[136:137], v[104:105], v[32:33]
	s_waitcnt vmcnt(5)
	v_lshlrev_b32_e32 v32, 16, v44
	v_and_b32_e32 v33, 0xffff0000, v44
	v_lshlrev_b32_e32 v28, 16, v45
	v_and_b32_e32 v29, 0xffff0000, v45
	v_pk_mul_f32 v[32:33], v[0:1], v[32:33] op_sel_hi:[0,1]
	v_pk_mul_f32 v[28:29], v[0:1], v[28:29] op_sel_hi:[0,1]
	v_pk_mul_f32 v[142:143], v[110:111], v[28:29]
	v_pk_mul_f32 v[140:141], v[108:109], v[32:33]
	s_waitcnt vmcnt(4)
	v_lshlrev_b32_e32 v32, 16, v46
	v_and_b32_e32 v33, 0xffff0000, v46
	v_lshlrev_b32_e32 v28, 16, v47
	v_and_b32_e32 v29, 0xffff0000, v47
	v_pk_mul_f32 v[32:33], v[0:1], v[32:33] op_sel_hi:[0,1]
	v_pk_mul_f32 v[28:29], v[0:1], v[28:29] op_sel_hi:[0,1]
	v_pk_mul_f32 v[146:147], v[114:115], v[28:29]
	v_pk_mul_f32 v[144:145], v[112:113], v[32:33]
	s_waitcnt vmcnt(3)
	v_lshlrev_b32_e32 v32, 16, v48
	v_and_b32_e32 v33, 0xffff0000, v48
	v_lshlrev_b32_e32 v28, 16, v49
	v_and_b32_e32 v29, 0xffff0000, v49
	v_pk_mul_f32 v[32:33], v[0:1], v[32:33] op_sel_hi:[0,1]
	v_pk_mul_f32 v[28:29], v[0:1], v[28:29] op_sel_hi:[0,1]
	v_pk_mul_f32 v[150:151], v[118:119], v[28:29]
	v_pk_mul_f32 v[148:149], v[116:117], v[32:33]
	s_waitcnt vmcnt(2)
	v_lshlrev_b32_e32 v32, 16, v50
	v_and_b32_e32 v33, 0xffff0000, v50
	v_lshlrev_b32_e32 v28, 16, v51
	v_and_b32_e32 v29, 0xffff0000, v51
	v_pk_mul_f32 v[32:33], v[0:1], v[32:33] op_sel_hi:[0,1]
	v_pk_mul_f32 v[28:29], v[0:1], v[28:29] op_sel_hi:[0,1]
	v_pk_mul_f32 v[154:155], v[122:123], v[28:29]
	v_pk_mul_f32 v[152:153], v[120:121], v[32:33]
	s_waitcnt vmcnt(1)
	v_lshlrev_b32_e32 v32, 16, v52
	v_and_b32_e32 v33, 0xffff0000, v52
	v_lshlrev_b32_e32 v28, 16, v53
	v_and_b32_e32 v29, 0xffff0000, v53
	v_pk_mul_f32 v[32:33], v[0:1], v[32:33] op_sel_hi:[0,1]
	v_pk_mul_f32 v[28:29], v[0:1], v[28:29] op_sel_hi:[0,1]
	v_pk_mul_f32 v[158:159], v[126:127], v[28:29]
	v_pk_mul_f32 v[156:157], v[124:125], v[32:33]
	s_waitcnt vmcnt(0)
	v_lshlrev_b32_e32 v32, 16, v54
	v_and_b32_e32 v33, 0xffff0000, v54
	v_lshlrev_b32_e32 v28, 16, v55
	v_and_b32_e32 v29, 0xffff0000, v55
	v_pk_mul_f32 v[32:33], v[0:1], v[32:33] op_sel_hi:[0,1]
	v_pk_mul_f32 v[28:29], v[0:1], v[28:29] op_sel_hi:[0,1]
	v_pk_mul_f32 v[162:163], v[130:131], v[28:29]
	v_pk_mul_f32 v[160:161], v[128:129], v[32:33]
	global_store_dwordx4 v[30:31], v[132:135], off offset:-3072
	global_store_dwordx4 v[30:31], v[136:139], off offset:-2048
	global_store_dwordx4 v[30:31], v[140:143], off offset:-1024
	global_store_dwordx4 v[14:15], v[144:147], off offset:-4096
	global_store_dwordx4 v[14:15], v[148:151], off offset:-3072
	global_store_dwordx4 v[14:15], v[152:155], off offset:-2048
	global_store_dwordx4 v[14:15], v[156:159], off offset:-1024
	global_store_dwordx4 v[14:15], v[160:163], off
	v_lshl_add_u64 v[14:15], v[14:15], 0, s[18:19]
	s_cmpk_gt_i32 s4, 0x3fff
	s_cbranch_scc0 .LBB0_27
	s_branch .LBB0_32
